# B/C attention loops: s_setprio 1 around the QK and PV MFMA clusters, 0 elsewhere
# baseline (speedup 1.0000x reference)
; template <int MODE>
; __device__ __forceinline__ void attn_item_BC(const Params& p, int layer, int head, int q0u, char* lds) {
;     ...
;   for (int t = 0; t < ntiles; ++t) {
;     const int buf = t & 1;
;     const bool more = (t + 1 < ntiles);
;     if (more) { ATT_LOADK(t + 1); ATT_LOADV(t + 1); }
;     const bool local = t >= 8;
;     const int kp0 = lo + (t - 8) * 32;
;     f32x16 sx;
;     ATT_SCORES(sx, 0, 8);
.LBB0_1517:
	s_and_b32 s52, s4, 1
	s_mul_i32 s0, s52, 0x2200
	v_add_u32_e32 v138, s0, v147
	ds_read_b128 v[64:67], v138
	ds_read_b128 v[150:153], v138 offset:32
	s_sub_i32 s0, s49, 32
	s_cmp_gt_u32 s4, 7
	s_cselect_b64 s[10:11], -1, 0
	s_setprio 1
	s_waitcnt lgkmcnt(1)
	v_mfma_f32_32x32x16_bf16 v[64:79], v[64:67], v[80:83], 0
	s_add_i32 s1, s5, 0xfffffee0
	s_ashr_i32 s5, s1, 6
	v_and_or_b32 v149, s0, 32, v133
	s_cmp_lt_u32 s4, 8
	s_waitcnt lgkmcnt(0)
	v_mfma_f32_32x32x16_bf16 v[64:79], v[150:153], v[84:87], v[64:79]
	ds_read_b128 v[150:153], v138 offset:64
	ds_read_b128 v[154:157], v138 offset:96
	s_waitcnt lgkmcnt(1)
	v_mfma_f32_32x32x16_bf16 v[64:79], v[150:153], v[88:91], v[64:79]
	s_waitcnt lgkmcnt(0)
	v_mfma_f32_32x32x16_bf16 v[64:79], v[154:157], v[92:95], v[64:79]
	ds_read_b128 v[150:153], v138 offset:128
	ds_read_b128 v[154:157], v138 offset:160
	s_waitcnt lgkmcnt(1)
	v_mfma_f32_32x32x16_bf16 v[64:79], v[150:153], v[96:99], v[64:79]
	s_waitcnt lgkmcnt(0)
	v_mfma_f32_32x32x16_bf16 v[64:79], v[154:157], v[100:103], v[64:79]
	ds_read_b128 v[150:153], v138 offset:192
	ds_read_b128 v[154:157], v138 offset:224
	v_sub_u32_e32 v138, s5, v144
	v_cmp_gt_u32_e64 s[0:1], 8, v138
	v_sub_u32_e32 v138, s5, v143
	v_mad_u64_u32 v[138:139], s[4:5], v138, 31, v[128:129]
	s_waitcnt lgkmcnt(1)
	v_mfma_f32_32x32x16_bf16 v[64:79], v[150:153], v[104:107], v[64:79]
	s_waitcnt lgkmcnt(0)
	v_mfma_f32_32x32x16_bf16 v[64:79], v[154:157], v[108:111], v[64:79]
	s_setprio 0
	s_cbranch_scc1 .LBB0_1549
	v_mov_b32_e32 v240, v149
	v_sub_u32_e32 v150, v240, v142
	v_cmp_gt_u32_e32 vcc, 16, v150
	v_add_u32_e32 v240, v138, v240
	s_and_b64 vcc, s[0:1], vcc
	v_cndmask_b32_e32 v240, 0, v240, vcc
	v_lshlrev_b32_e32 v240, 2, v240
	ds_read_b32 v240, v240 offset:35840
	v_or_b32_e32 v241, 1, v149
	v_sub_u32_e32 v150, v241, v142
	v_cmp_gt_u32_e32 vcc, 16, v150
	v_add_u32_e32 v241, v138, v241
	s_and_b64 vcc, s[0:1], vcc
	v_cndmask_b32_e32 v241, 0, v241, vcc
	v_lshlrev_b32_e32 v241, 2, v241
	ds_read_b32 v241, v241 offset:35840
	v_or_b32_e32 v242, 2, v149
	v_sub_u32_e32 v150, v242, v142
	v_cmp_gt_u32_e32 vcc, 16, v150
	v_add_u32_e32 v242, v138, v242
	s_and_b64 vcc, s[0:1], vcc
	v_cndmask_b32_e32 v242, 0, v242, vcc
	v_lshlrev_b32_e32 v242, 2, v242
	ds_read_b32 v242, v242 offset:35840
	v_or_b32_e32 v243, 3, v149
	v_sub_u32_e32 v150, v243, v142
	v_cmp_gt_u32_e32 vcc, 16, v150
	v_add_u32_e32 v243, v138, v243
	s_and_b64 vcc, s[0:1], vcc
	v_cndmask_b32_e32 v243, 0, v243, vcc
	v_lshlrev_b32_e32 v243, 2, v243
	ds_read_b32 v243, v243 offset:35840
	v_or_b32_e32 v244, 8, v149
	v_sub_u32_e32 v150, v244, v142
	v_cmp_gt_u32_e32 vcc, 16, v150
	v_add_u32_e32 v244, v138, v244
	s_and_b64 vcc, s[0:1], vcc
	v_cndmask_b32_e32 v244, 0, v244, vcc
	v_lshlrev_b32_e32 v244, 2, v244
	ds_read_b32 v244, v244 offset:35840
	v_or_b32_e32 v245, 9, v149
	v_sub_u32_e32 v150, v245, v142
	v_cmp_gt_u32_e32 vcc, 16, v150
	v_add_u32_e32 v245, v138, v245
	s_and_b64 vcc, s[0:1], vcc
	v_cndmask_b32_e32 v245, 0, v245, vcc
	v_lshlrev_b32_e32 v245, 2, v245
	ds_read_b32 v245, v245 offset:35840
	v_or_b32_e32 v246, 10, v149
	v_sub_u32_e32 v150, v246, v142
	v_cmp_gt_u32_e32 vcc, 16, v150
	v_add_u32_e32 v246, v138, v246
	s_and_b64 vcc, s[0:1], vcc
	v_cndmask_b32_e32 v246, 0, v246, vcc
	v_lshlrev_b32_e32 v246, 2, v246
	ds_read_b32 v246, v246 offset:35840
	v_or_b32_e32 v247, 11, v149
	v_sub_u32_e32 v150, v247, v142
	v_cmp_gt_u32_e32 vcc, 16, v150
	v_add_u32_e32 v247, v138, v247
	s_and_b64 vcc, s[0:1], vcc
	v_cndmask_b32_e32 v247, 0, v247, vcc
	v_lshlrev_b32_e32 v247, 2, v247
	ds_read_b32 v247, v247 offset:35840
	v_or_b32_e32 v248, 16, v149
	v_sub_u32_e32 v150, v248, v142
	v_cmp_gt_u32_e32 vcc, 16, v150
	v_add_u32_e32 v248, v138, v248
	s_and_b64 vcc, s[0:1], vcc
	v_cndmask_b32_e32 v248, 0, v248, vcc
	v_lshlrev_b32_e32 v248, 2, v248
	ds_read_b32 v248, v248 offset:35840
	v_or_b32_e32 v249, 17, v149
	v_sub_u32_e32 v150, v249, v142
	v_cmp_gt_u32_e32 vcc, 16, v150
	v_add_u32_e32 v249, v138, v249
	s_and_b64 vcc, s[0:1], vcc
	v_cndmask_b32_e32 v249, 0, v249, vcc
	v_lshlrev_b32_e32 v249, 2, v249
	ds_read_b32 v249, v249 offset:35840
	v_or_b32_e32 v250, 18, v149
	v_sub_u32_e32 v150, v250, v142
	v_cmp_gt_u32_e32 vcc, 16, v150
	v_add_u32_e32 v250, v138, v250
	s_and_b64 vcc, s[0:1], vcc
	v_cndmask_b32_e32 v250, 0, v250, vcc
	v_lshlrev_b32_e32 v250, 2, v250
	ds_read_b32 v250, v250 offset:35840
	v_or_b32_e32 v251, 19, v149
	v_sub_u32_e32 v150, v251, v142
	v_cmp_gt_u32_e32 vcc, 16, v150
	v_add_u32_e32 v251, v138, v251
	s_and_b64 vcc, s[0:1], vcc
	v_cndmask_b32_e32 v251, 0, v251, vcc
	v_lshlrev_b32_e32 v251, 2, v251
	ds_read_b32 v251, v251 offset:35840
	v_or_b32_e32 v252, 24, v149
	v_sub_u32_e32 v150, v252, v142
	v_cmp_gt_u32_e32 vcc, 16, v150
	v_add_u32_e32 v252, v138, v252
	s_and_b64 vcc, s[0:1], vcc
	v_cndmask_b32_e32 v252, 0, v252, vcc
	v_lshlrev_b32_e32 v252, 2, v252
	ds_read_b32 v252, v252 offset:35840
	v_or_b32_e32 v253, 25, v149
	v_sub_u32_e32 v150, v253, v142
	v_cmp_gt_u32_e32 vcc, 16, v150
	v_add_u32_e32 v253, v138, v253
	s_and_b64 vcc, s[0:1], vcc
	v_cndmask_b32_e32 v253, 0, v253, vcc
	v_lshlrev_b32_e32 v253, 2, v253
	ds_read_b32 v253, v253 offset:35840
	v_or_b32_e32 v254, 26, v149
	v_sub_u32_e32 v150, v254, v142
	v_cmp_gt_u32_e32 vcc, 16, v150
	v_add_u32_e32 v254, v138, v254
	s_and_b64 vcc, s[0:1], vcc
	v_cndmask_b32_e32 v254, 0, v254, vcc
	v_lshlrev_b32_e32 v254, 2, v254
	ds_read_b32 v254, v254 offset:35840
	v_or_b32_e32 v255, 27, v149
	v_sub_u32_e32 v150, v255, v142
	v_cmp_gt_u32_e32 vcc, 16, v150
	v_add_u32_e32 v255, v138, v255
	s_and_b64 vcc, s[0:1], vcc
	v_cndmask_b32_e32 v255, 0, v255, vcc
	v_lshlrev_b32_e32 v255, 2, v255
	ds_read_b32 v255, v255 offset:35840
	s_waitcnt lgkmcnt(0)
; #define MFMA32(a, b, c) __builtin_amdgcn_mfma_f32_32x32x16_bf16((a), (b), (c), 0, 0, 0)
; DI unsigned pk2(float a, float b) { f32x2 v = {a, b}; bf2_t r = __builtin_convertvector(v, bf2_t); return __builtin_bit_cast(unsigned, r); }
; template <int MODE>
; __device__ __forceinline__ void attn_item_BC(const Params& p, int layer, int head, int q0u, char* lds) {
;     ...
;     ATT_SCORES(sx, 0, 8);
;     float w[16];
; #pragma unroll
;     for (int e = 0; e < 16; ++e) { w[e] = __builtin_amdgcn_exp2f(fmaf(sx[e], CS, -bsh)); lA += w[e]; }
;     const u32x4 p0 = {pk2(w[0], w[1]), pk2(w[2], w[3]), pk2(w[4], w[5]), pk2(w[6], w[7])};
;     const u32x4 p1 = {pk2(w[8], w[9]), pk2(w[10], w[11]), pk2(w[12], w[13]), pk2(w[14], w[15])};
;     const bf16x8 pa0 = __builtin_bit_cast(bf16x8, p0), pa1 = __builtin_bit_cast(bf16x8, p1);
;     const u16* vt = Vt + buf * 128 * VLD + r * VLD + 4 * h;
; #pragma unroll
;     for (int d = 0; d < 4; ++d) {
;       const s16x4 l0 = *(const s16x4*)(vt + d * 32 * VLD), h0 = *(const s16x4*)(vt + d * 32 * VLD + 8);
;       const s16x4 l1 = *(const s16x4*)(vt + d * 32 * VLD + 16), h1 = *(const s16x4*)(vt + d * 32 * VLD + 24);
;       const bf16x8 v0 = {l0[0], l0[1], l0[2], l0[3], h0[0], h0[1], h0[2], h0[3]};
;       const bf16x8 v1 = {l1[0], l1[1], l1[2], l1[3], h1[0], h1[1], h1[2], h1[3]};
;       o[d] = MFMA32(pa0, v0, o[d]);
;       o[d] = MFMA32(pa1, v1, o[d]);
;     }
;     if (more) { ATT_STOREK(buf ^ 1); ATT_STOREV(buf ^ 1); }
	v_mov_b32_e32 v139, v149
	v_sub_u32_e32 v150, v139, v142
	v_cmp_gt_u32_e32 vcc, 16, v150
	v_add_f32_e32 v64, v64, v240
	s_and_b64 vcc, s[0:1], vcc
	v_cndmask_b32_e32 v64, v189, v64, vcc
	v_or_b32_e32 v139, 1, v149
	v_sub_u32_e32 v150, v139, v142
	v_cmp_gt_u32_e32 vcc, 16, v150
	v_add_f32_e32 v65, v65, v241
	s_and_b64 vcc, s[0:1], vcc
	v_cndmask_b32_e32 v65, v189, v65, vcc
	v_or_b32_e32 v139, 2, v149
	v_sub_u32_e32 v150, v139, v142
	v_cmp_gt_u32_e32 vcc, 16, v150
	v_add_f32_e32 v66, v66, v242
	s_and_b64 vcc, s[0:1], vcc
	v_cndmask_b32_e32 v66, v189, v66, vcc
	v_or_b32_e32 v139, 3, v149
	v_sub_u32_e32 v150, v139, v142
	v_cmp_gt_u32_e32 vcc, 16, v150
	v_add_f32_e32 v67, v67, v243
	s_and_b64 vcc, s[0:1], vcc
	v_cndmask_b32_e32 v67, v189, v67, vcc
	v_or_b32_e32 v139, 8, v149
	v_sub_u32_e32 v150, v139, v142
	v_cmp_gt_u32_e32 vcc, 16, v150
	v_add_f32_e32 v68, v68, v244
	s_and_b64 vcc, s[0:1], vcc
	v_cndmask_b32_e32 v68, v189, v68, vcc
	v_or_b32_e32 v139, 9, v149
	v_sub_u32_e32 v150, v139, v142
	v_cmp_gt_u32_e32 vcc, 16, v150
	v_add_f32_e32 v69, v69, v245
	s_and_b64 vcc, s[0:1], vcc
	v_cndmask_b32_e32 v69, v189, v69, vcc
	v_or_b32_e32 v139, 10, v149
	v_sub_u32_e32 v150, v139, v142
	v_cmp_gt_u32_e32 vcc, 16, v150
	v_add_f32_e32 v70, v70, v246
	s_and_b64 vcc, s[0:1], vcc
	v_cndmask_b32_e32 v70, v189, v70, vcc
	v_or_b32_e32 v139, 11, v149
	v_sub_u32_e32 v150, v139, v142
	v_cmp_gt_u32_e32 vcc, 16, v150
	v_add_f32_e32 v71, v71, v247
	s_and_b64 vcc, s[0:1], vcc
	v_cndmask_b32_e32 v71, v189, v71, vcc
	v_or_b32_e32 v139, 16, v149
	v_sub_u32_e32 v150, v139, v142
	v_cmp_gt_u32_e32 vcc, 16, v150
	v_add_f32_e32 v72, v72, v248
	s_and_b64 vcc, s[0:1], vcc
	v_cndmask_b32_e32 v72, v189, v72, vcc
	v_or_b32_e32 v139, 17, v149
	v_sub_u32_e32 v150, v139, v142
	v_cmp_gt_u32_e32 vcc, 16, v150
	v_add_f32_e32 v73, v73, v249
	s_and_b64 vcc, s[0:1], vcc
	v_cndmask_b32_e32 v73, v189, v73, vcc
	v_or_b32_e32 v139, 18, v149
	v_sub_u32_e32 v150, v139, v142
	v_cmp_gt_u32_e32 vcc, 16, v150
	v_add_f32_e32 v74, v74, v250
	s_and_b64 vcc, s[0:1], vcc
	v_cndmask_b32_e32 v74, v189, v74, vcc
	v_or_b32_e32 v139, 19, v149
	v_sub_u32_e32 v150, v139, v142
	v_cmp_gt_u32_e32 vcc, 16, v150
	v_add_f32_e32 v75, v75, v251
	s_and_b64 vcc, s[0:1], vcc
	v_cndmask_b32_e32 v75, v189, v75, vcc
	v_or_b32_e32 v139, 24, v149
	v_sub_u32_e32 v150, v139, v142
	v_cmp_gt_u32_e32 vcc, 16, v150
	v_add_f32_e32 v76, v76, v252
	s_and_b64 vcc, s[0:1], vcc
	v_cndmask_b32_e32 v76, v189, v76, vcc
	v_or_b32_e32 v139, 25, v149
	v_sub_u32_e32 v150, v139, v142
	v_cmp_gt_u32_e32 vcc, 16, v150
	v_add_f32_e32 v77, v77, v253
	s_and_b64 vcc, s[0:1], vcc
	v_cndmask_b32_e32 v77, v189, v77, vcc
	v_or_b32_e32 v139, 26, v149
	v_sub_u32_e32 v150, v139, v142
	v_cmp_gt_u32_e32 vcc, 16, v150
	v_add_f32_e32 v78, v78, v254
	s_and_b64 vcc, s[0:1], vcc
	v_cndmask_b32_e32 v78, v189, v78, vcc
	v_or_b32_e32 v139, 27, v149
	v_sub_u32_e32 v150, v139, v142
	v_cmp_gt_u32_e32 vcc, 16, v150
	v_add_f32_e32 v79, v79, v255
	s_and_b64 vcc, s[0:1], vcc
	v_cndmask_b32_e32 v79, v189, v79, vcc
.LBB0_1549:
	v_fma_f32 v64, v64, s71, -v146
	v_fma_f32 v65, v65, s71, -v146
	v_fma_f32 v66, v66, s71, -v146
	v_fma_f32 v67, v67, s71, -v146
	v_fma_f32 v68, v68, s71, -v146
	v_fma_f32 v69, v69, s71, -v146
	v_fma_f32 v70, v70, s71, -v146
	v_fma_f32 v71, v71, s71, -v146
	v_exp_f32_e32 v64, v64
	v_exp_f32_e32 v65, v65
	v_exp_f32_e32 v66, v66
	v_exp_f32_e32 v67, v67
	v_exp_f32_e32 v68, v68
	v_exp_f32_e32 v69, v69
	v_exp_f32_e32 v70, v70
	v_exp_f32_e32 v71, v71
	s_mul_i32 s0, s52, 0x2400
	v_add_u32_e32 v138, s0, v148
	v_add_u32_e32 v139, 0x4000, v138
	v_cvt_pk_bf16_f32 v150, v64, v65
	v_cvt_pk_bf16_f32 v151, v66, v67
	v_cvt_pk_bf16_f32 v152, v68, v69
	v_cvt_pk_bf16_f32 v153, v70, v71
	ds_read2_b64 v[154:157], v139 offset0:128 offset1:130
	v_fma_f32 v72, v72, s71, -v146
	v_fma_f32 v73, v73, s71, -v146
	v_fma_f32 v74, v74, s71, -v146
	v_fma_f32 v75, v75, s71, -v146
	v_fma_f32 v76, v76, s71, -v146
	v_fma_f32 v77, v77, s71, -v146
	v_fma_f32 v78, v78, s71, -v146
	v_fma_f32 v79, v79, s71, -v146
	v_exp_f32_e32 v72, v72
	v_exp_f32_e32 v73, v73
	v_exp_f32_e32 v74, v74
	v_exp_f32_e32 v75, v75
	v_exp_f32_e32 v76, v76
	v_exp_f32_e32 v77, v77
	v_exp_f32_e32 v78, v78
	v_exp_f32_e32 v79, v79
	s_setprio 1
	s_waitcnt lgkmcnt(0)
	v_mfma_f32_32x32x16_bf16 v[48:63], v[150:153], v[154:157], v[48:63]
	v_cvt_pk_bf16_f32 v158, v72, v73
	v_cvt_pk_bf16_f32 v159, v74, v75
	v_cvt_pk_bf16_f32 v160, v76, v77
	v_cvt_pk_bf16_f32 v161, v78, v79
	ds_read2_b64 v[154:157], v139 offset0:132 offset1:134
	v_add_u32_e32 v139, 0x4800, v138
	s_andn2_b64 vcc, exec, s[8:9]
	s_waitcnt lgkmcnt(0)
	v_mfma_f32_32x32x16_bf16 v[48:63], v[158:161], v[154:157], v[48:63]
	ds_read2_b64 v[154:157], v139 offset0:160 offset1:162
	s_waitcnt lgkmcnt(0)
	v_mfma_f32_32x32x16_bf16 v[32:47], v[150:153], v[154:157], v[32:47]
	ds_read2_b64 v[154:157], v139 offset0:164 offset1:166
	v_add_u32_e32 v139, 0x5000, v138
	v_add_u32_e32 v138, 0x5800, v138
	s_waitcnt lgkmcnt(0)
	v_mfma_f32_32x32x16_bf16 v[32:47], v[158:161], v[154:157], v[32:47]
	ds_read2_b64 v[154:157], v139 offset0:192 offset1:194
	s_waitcnt lgkmcnt(0)
	v_mfma_f32_32x32x16_bf16 v[16:31], v[150:153], v[154:157], v[16:31]
	ds_read2_b64 v[154:157], v139 offset0:196 offset1:198
	s_waitcnt lgkmcnt(0)
	v_mfma_f32_32x32x16_bf16 v[16:31], v[158:161], v[154:157], v[16:31]
	ds_read2_b64 v[154:157], v138 offset0:224 offset1:226
	s_waitcnt lgkmcnt(0)
	v_mfma_f32_32x32x16_bf16 v[0:15], v[150:153], v[154:157], v[0:15]
	ds_read2_b64 v[150:153], v138 offset0:228 offset1:230
	s_waitcnt lgkmcnt(0)
	v_mfma_f32_32x32x16_bf16 v[0:15], v[158:161], v[150:153], v[0:15]
	s_setprio 0
	s_cbranch_vccnz .LBB0_1551
	s_xor_b32 s0, s52, 1
	s_mul_i32 s1, s0, 0x2200
	v_add_u32_e32 v138, s1, v134
	s_mulk_i32 s0, 0x2400
	s_waitcnt vmcnt(2)
	ds_write_b128 v138, v[116:119]
	ds_write_b128 v138, v[112:115] offset:16
	v_add_u32_e32 v138, s0, v132
	v_add_u32_e32 v139, 0x4400, v138
	v_add_u32_e32 v138, 0x4410, v138
	s_waitcnt vmcnt(0)
	ds_write2_b64 v139, v[124:125], v[126:127] offset1:1
	ds_write2_b64 v138, v[120:121], v[122:123] offset1:1

; #define MFMA32(a, b, c) __builtin_amdgcn_mfma_f32_32x32x16_bf16((a), (b), (c), 0, 0, 0)
; DI unsigned pk2(float a, float b) { f32x2 v = {a, b}; bf2_t r = __builtin_convertvector(v, bf2_t); return __builtin_bit_cast(unsigned, r); }
; template <int MODE>
; __device__ __forceinline__ void attn_item_BC(const Params& p, int layer, int head, int q0u, char* lds) {
;     ...
;     const int buf = t & 1;
;     const bool more = (t + 1 < ntiles);
;     if (more) { ATT_LOADK(t + 1); ATT_LOADV(t + 1); }
;     const bool local = t >= 8;
;     const int kp0 = lo + (t - 8) * 32;
;     f32x16 sx;
;     ATT_SCORES(sx, 0, 8);
;     float w[16];
; #pragma unroll
;     for (int e = 0; e < 16; ++e) { w[e] = __builtin_amdgcn_exp2f(fmaf(sx[e], CS, -bsh)); lA += w[e]; }
;     const u32x4 p0 = {pk2(w[0], w[1]), pk2(w[2], w[3]), pk2(w[4], w[5]), pk2(w[6], w[7])};
;     const u32x4 p1 = {pk2(w[8], w[9]), pk2(w[10], w[11]), pk2(w[12], w[13]), pk2(w[14], w[15])};
;     const bf16x8 pa0 = __builtin_bit_cast(bf16x8, p0), pa1 = __builtin_bit_cast(bf16x8, p1);
;     const u16* vt = Vt + buf * 128 * VLD + r * VLD + 4 * h;
; #pragma unroll
;     for (int d = 0; d < 4; ++d) {
;       const s16x4 l0 = *(const s16x4*)(vt + d * 32 * VLD), h0 = *(const s16x4*)(vt + d * 32 * VLD + 8);
;       const s16x4 l1 = *(const s16x4*)(vt + d * 32 * VLD + 16), h1 = *(const s16x4*)(vt + d * 32 * VLD + 24);
;       const bf16x8 v0 = {l0[0], l0[1], l0[2], l0[3], h0[0], h0[1], h0[2], h0[3]};
;       const bf16x8 v1 = {l1[0], l1[1], l1[2], l1[3], h1[0], h1[1], h1[2], h1[3]};
;       o[d] = MFMA32(pa0, v0, o[d]);
;       o[d] = MFMA32(pa1, v1, o[d]);
;     }
;     if (more) { ATT_STOREK(buf ^ 1); ATT_STOREV(buf ^ 1); }
.LBB0_1563:
	s_and_b32 s9, s4, 1
	s_mul_i32 s10, s9, 0x2200
	v_add_u32_e32 v145, s10, v142
	ds_read_b128 v[64:67], v145
	ds_read_b128 v[146:149], v145 offset:32
	s_cmp_gt_u32 s4, 7
	s_cselect_b64 s[4:5], -1, 0
	s_setprio 1
	s_waitcnt lgkmcnt(1)
	v_mfma_f32_32x32x16_bf16 v[64:79], v[64:67], v[80:83], 0
	s_waitcnt lgkmcnt(0)
	v_mfma_f32_32x32x16_bf16 v[64:79], v[146:149], v[84:87], v[64:79]
	ds_read_b128 v[146:149], v145 offset:64
	s_waitcnt lgkmcnt(0)
	v_mfma_f32_32x32x16_bf16 v[64:79], v[146:149], v[88:91], v[64:79]
	ds_read_b128 v[146:149], v145 offset:96
	s_waitcnt lgkmcnt(0)
	v_mfma_f32_32x32x16_bf16 v[64:79], v[146:149], v[92:95], v[64:79]
	ds_read_b128 v[146:149], v145 offset:128
	s_waitcnt lgkmcnt(0)
	v_mfma_f32_32x32x16_bf16 v[64:79], v[146:149], v[96:99], v[64:79]
	ds_read_b128 v[146:149], v145 offset:160
	s_waitcnt lgkmcnt(0)
	v_mfma_f32_32x32x16_bf16 v[64:79], v[146:149], v[100:103], v[64:79]
	ds_read_b128 v[146:149], v145 offset:192
	s_waitcnt lgkmcnt(0)
	v_mfma_f32_32x32x16_bf16 v[64:79], v[146:149], v[116:119], v[64:79]
	ds_read_b128 v[146:149], v145 offset:224
	v_add_u32_e32 v145, s7, v144
	s_waitcnt lgkmcnt(0)
	v_mfma_f32_32x32x16_bf16 v[64:79], v[146:149], v[104:107], v[64:79]
	s_setprio 0
	v_add_u32_e32 v146, 0xffffff7f, v145
	v_cmp_gt_u32_e32 vcc, s79, v146
	s_and_b64 vcc, s[4:5], vcc
	v_add_u32_e32 v146, 0xffffff80, v145
	s_nop 7
	v_cndmask_b32_e32 v64, v64, v189, vcc
	v_cmp_gt_u32_e32 vcc, s79, v146
	s_and_b64 vcc, s[4:5], vcc
	v_add_u32_e32 v146, 0xffffff81, v145
	v_cndmask_b32_e32 v65, v65, v189, vcc
	v_cmp_gt_u32_e32 vcc, s79, v146
	s_and_b64 vcc, s[4:5], vcc
	v_add_u32_e32 v146, 0xffffff82, v145
	v_cndmask_b32_e32 v66, v66, v189, vcc
	v_cmp_gt_u32_e32 vcc, s79, v146
	s_and_b64 vcc, s[4:5], vcc
	v_add_u32_e32 v146, 0xffffff87, v145
	v_cndmask_b32_e32 v67, v67, v189, vcc
	v_cmp_gt_u32_e32 vcc, s79, v146
	s_and_b64 vcc, s[4:5], vcc
	v_add_u32_e32 v146, 0xffffff88, v145
	v_cndmask_b32_e32 v68, v68, v189, vcc
	v_cmp_gt_u32_e32 vcc, s79, v146
	s_and_b64 vcc, s[4:5], vcc
	v_add_u32_e32 v146, 0xffffff89, v145
	v_cndmask_b32_e32 v69, v69, v189, vcc
	v_cmp_gt_u32_e32 vcc, s79, v146
	s_and_b64 vcc, s[4:5], vcc
	v_add_u32_e32 v146, 0xffffff8a, v145
	v_cndmask_b32_e32 v70, v70, v189, vcc
	v_cmp_gt_u32_e32 vcc, s79, v146
	s_and_b64 vcc, s[4:5], vcc
	v_add_u32_e32 v146, 0xffffff8f, v145
	v_cndmask_b32_e32 v71, v71, v189, vcc
	v_cmp_gt_u32_e32 vcc, s79, v146
	s_and_b64 vcc, s[4:5], vcc
	v_add_u32_e32 v146, 0xffffff90, v145
	v_cndmask_b32_e32 v72, v72, v189, vcc
	v_cmp_gt_u32_e32 vcc, s79, v146
	s_and_b64 vcc, s[4:5], vcc
	v_add_u32_e32 v146, 0xffffff91, v145
	v_cndmask_b32_e32 v73, v73, v189, vcc
	v_cmp_gt_u32_e32 vcc, s79, v146
	s_and_b64 vcc, s[4:5], vcc
	v_add_u32_e32 v146, 0xffffff92, v145
	v_cndmask_b32_e32 v74, v74, v189, vcc
	v_cmp_gt_u32_e32 vcc, s79, v146
	s_and_b64 vcc, s[4:5], vcc
	v_add_u32_e32 v146, 0xffffff97, v145
	v_cndmask_b32_e32 v75, v75, v189, vcc
	v_cmp_gt_u32_e32 vcc, s79, v146
	s_and_b64 vcc, s[4:5], vcc
	v_add_u32_e32 v146, 0xffffff98, v145
	v_cndmask_b32_e32 v76, v76, v189, vcc
	v_cmp_gt_u32_e32 vcc, s79, v146
	s_and_b64 vcc, s[4:5], vcc
	v_add_u32_e32 v146, 0xffffff99, v145
	v_cndmask_b32_e32 v77, v77, v189, vcc
	v_cmp_gt_u32_e32 vcc, s79, v146
	v_fma_f32 v64, v64, s71, -v139
	v_fma_f32 v65, v65, s71, -v139
	v_fma_f32 v66, v66, s71, -v139
	v_fma_f32 v67, v67, s71, -v139
	v_fma_f32 v68, v68, s71, -v139
	v_fma_f32 v69, v69, s71, -v139
	v_fma_f32 v70, v70, s71, -v139
	v_fma_f32 v71, v71, s71, -v139
	s_and_b64 vcc, s[4:5], vcc
	v_add_u32_e32 v145, 0xffffff9a, v145
	v_exp_f32_e32 v64, v64
	v_exp_f32_e32 v65, v65
	v_exp_f32_e32 v66, v66
	v_exp_f32_e32 v67, v67
	v_exp_f32_e32 v68, v68
	v_exp_f32_e32 v69, v69
	v_exp_f32_e32 v70, v70
	v_exp_f32_e32 v71, v71
	v_cndmask_b32_e32 v78, v78, v189, vcc
	v_cmp_gt_u32_e32 vcc, s79, v145
	s_and_b64 vcc, s[4:5], vcc
	s_mul_i32 s4, s9, 0x2400
	v_add_u32_e32 v145, s4, v143
	v_cvt_pk_bf16_f32 v146, v64, v65
	v_cvt_pk_bf16_f32 v147, v66, v67
	v_cvt_pk_bf16_f32 v148, v68, v69
	v_cvt_pk_bf16_f32 v149, v70, v71
	v_add_u32_e32 v158, 0x4000, v145
	ds_read2_b64 v[154:157], v158 offset0:128 offset1:130
	ds_read2_b64 v[158:161], v158 offset0:132 offset1:134
	v_cndmask_b32_e32 v79, v79, v189, vcc
	v_fma_f32 v72, v72, s71, -v139
	v_fma_f32 v73, v73, s71, -v139
	v_fma_f32 v74, v74, s71, -v139
	v_fma_f32 v75, v75, s71, -v139
	v_fma_f32 v76, v76, s71, -v139
	v_fma_f32 v77, v77, s71, -v139
	v_fma_f32 v78, v78, s71, -v139
	v_fma_f32 v79, v79, s71, -v139
	v_exp_f32_e32 v72, v72
	v_exp_f32_e32 v73, v73
	v_exp_f32_e32 v74, v74
	v_exp_f32_e32 v75, v75
	v_exp_f32_e32 v76, v76
	v_exp_f32_e32 v77, v77
	v_exp_f32_e32 v78, v78
	v_exp_f32_e32 v79, v79
	s_setprio 1
	s_waitcnt lgkmcnt(1)
	v_mfma_f32_32x32x16_bf16 v[48:63], v[146:149], v[154:157], v[48:63]
	v_cvt_pk_bf16_f32 v150, v72, v73
	v_cvt_pk_bf16_f32 v151, v74, v75
	v_cvt_pk_bf16_f32 v152, v76, v77
	v_cvt_pk_bf16_f32 v153, v78, v79
	s_andn2_b64 vcc, exec, s[0:1]
	s_waitcnt lgkmcnt(0)
	v_mfma_f32_32x32x16_bf16 v[48:63], v[150:153], v[158:161], v[48:63]
	v_add_u32_e32 v158, 0x4800, v145
	ds_read2_b64 v[154:157], v158 offset0:160 offset1:162
	ds_read2_b64 v[158:161], v158 offset0:164 offset1:166
	s_waitcnt lgkmcnt(1)
	v_mfma_f32_32x32x16_bf16 v[32:47], v[146:149], v[154:157], v[32:47]
	s_waitcnt lgkmcnt(0)
	v_mfma_f32_32x32x16_bf16 v[32:47], v[150:153], v[158:161], v[32:47]
	v_add_u32_e32 v158, 0x5000, v145
	ds_read2_b64 v[154:157], v158 offset0:192 offset1:194
	ds_read2_b64 v[158:161], v158 offset0:196 offset1:198
	v_add_u32_e32 v145, 0x5800, v145
	s_waitcnt lgkmcnt(1)
	v_mfma_f32_32x32x16_bf16 v[16:31], v[146:149], v[154:157], v[16:31]
	s_waitcnt lgkmcnt(0)
	v_mfma_f32_32x32x16_bf16 v[16:31], v[150:153], v[158:161], v[16:31]
	ds_read2_b64 v[154:157], v145 offset0:224 offset1:226
	ds_read2_b64 v[158:161], v145 offset0:228 offset1:230
	s_waitcnt lgkmcnt(1)
	v_mfma_f32_32x32x16_bf16 v[0:15], v[146:149], v[154:157], v[0:15]
	s_waitcnt lgkmcnt(0)
	v_mfma_f32_32x32x16_bf16 v[0:15], v[150:153], v[158:161], v[0:15]
	s_setprio 0
	s_cbranch_vccnz .LBB0_1565
	s_xor_b32 s0, s9, 1
	s_mul_i32 s1, s0, 0x2200
	v_add_u32_e32 v145, s1, v130
	s_mulk_i32 s0, 0x2400
	s_waitcnt vmcnt(2)
	ds_write_b128 v145, v[108:111]
	ds_write_b128 v145, v[112:115] offset:16
	v_add_u32_e32 v145, s0, v132
	v_add_u32_e32 v146, 0x4400, v145
	v_add_u32_e32 v145, 0x4410, v145
	s_waitcnt vmcnt(0)
	ds_write2_b64 v146, v[124:125], v[126:127] offset1:1
	ds_write2_b64 v145, v[120:121], v[122:123] offset1:1

; template <int MODE>
; __device__ __forceinline__ void attn_item_BC(const Params& p, int layer, int head, int q0u, char* lds) {
;     ...
;     const int buf = t & 1;
;     const bool more = (t + 1 < ntiles);
;     if (more) { ATT_LOADK(t + 1); ATT_LOADV(t + 1); }
;     const bool local = t >= 8;
;     const int kp0 = lo + (t - 8) * 32;
;     f32x16 sx;
;     ATT_SCORES(sx, 0, 8);
.LBB0_2273:
	s_and_b32 s52, s4, 1
	s_mul_i32 s0, s52, 0x2200
	v_add_u32_e32 v147, s0, v145
	ds_read_b128 v[64:67], v147
	ds_read_b128 v[148:151], v147 offset:32
	s_sub_i32 s0, s12, 32
	s_cmp_gt_u32 s4, 7
	s_cselect_b64 s[8:9], -1, 0
	s_setprio 1
	s_waitcnt lgkmcnt(1)
	v_mfma_f32_32x32x16_bf16 v[64:79], v[64:67], v[80:83], 0
	s_add_i32 s1, s5, 0xfffffee0
	s_ashr_i32 s5, s1, 6
	s_cmp_lt_u32 s4, 8
	s_waitcnt lgkmcnt(0)
	v_mfma_f32_32x32x16_bf16 v[64:79], v[148:151], v[84:87], v[64:79]
	ds_read_b128 v[148:151], v147 offset:64
	ds_read_b128 v[152:155], v147 offset:96
	s_waitcnt lgkmcnt(1)
	v_mfma_f32_32x32x16_bf16 v[64:79], v[148:151], v[88:91], v[64:79]
	s_waitcnt lgkmcnt(0)
	v_mfma_f32_32x32x16_bf16 v[64:79], v[152:155], v[92:95], v[64:79]
	ds_read_b128 v[148:151], v147 offset:128
	ds_read_b128 v[152:155], v147 offset:160
	s_waitcnt lgkmcnt(1)
	v_mfma_f32_32x32x16_bf16 v[64:79], v[148:151], v[96:99], v[64:79]
	s_waitcnt lgkmcnt(0)
	v_mfma_f32_32x32x16_bf16 v[64:79], v[152:155], v[100:103], v[64:79]
	ds_read_b128 v[148:151], v147 offset:192
	ds_read_b128 v[152:155], v147 offset:224
	v_and_or_b32 v147, s0, 32, v131
	s_waitcnt lgkmcnt(1)
	v_mfma_f32_32x32x16_bf16 v[64:79], v[148:151], v[104:107], v[64:79]
	v_sub_u32_e32 v148, s5, v142
	v_cmp_gt_u32_e64 s[0:1], 8, v148
	v_sub_u32_e32 v148, s5, v140
	v_mul_lo_u32 v148, v148, 31
	v_sub_u32_e32 v148, v148, v141
	v_add_u32_e32 v148, 0xe8, v148
	s_waitcnt lgkmcnt(0)
	v_mfma_f32_32x32x16_bf16 v[64:79], v[152:155], v[108:111], v[64:79]
	s_setprio 0
	s_cbranch_scc1 .LBB0_2305
	v_mov_b32_e32 v240, v147
	v_sub_u32_e32 v150, v240, v143
	v_cmp_gt_u32_e32 vcc, 16, v150
	v_add_u32_e32 v240, v148, v240
	s_and_b64 vcc, s[0:1], vcc
	v_cndmask_b32_e32 v240, 0, v240, vcc
	v_lshlrev_b32_e32 v240, 2, v240
	ds_read_b32 v240, v240 offset:35840
	v_or_b32_e32 v241, 1, v147
	v_sub_u32_e32 v150, v241, v143
	v_cmp_gt_u32_e32 vcc, 16, v150
	v_add_u32_e32 v241, v148, v241
	s_and_b64 vcc, s[0:1], vcc
	v_cndmask_b32_e32 v241, 0, v241, vcc
	v_lshlrev_b32_e32 v241, 2, v241
	ds_read_b32 v241, v241 offset:35840
	v_or_b32_e32 v242, 2, v147
	v_sub_u32_e32 v150, v242, v143
	v_cmp_gt_u32_e32 vcc, 16, v150
	v_add_u32_e32 v242, v148, v242
	s_and_b64 vcc, s[0:1], vcc
	v_cndmask_b32_e32 v242, 0, v242, vcc
	v_lshlrev_b32_e32 v242, 2, v242
	ds_read_b32 v242, v242 offset:35840
	v_or_b32_e32 v243, 3, v147
	v_sub_u32_e32 v150, v243, v143
	v_cmp_gt_u32_e32 vcc, 16, v150
	v_add_u32_e32 v243, v148, v243
	s_and_b64 vcc, s[0:1], vcc
	v_cndmask_b32_e32 v243, 0, v243, vcc
	v_lshlrev_b32_e32 v243, 2, v243
	ds_read_b32 v243, v243 offset:35840
	v_or_b32_e32 v244, 8, v147
	v_sub_u32_e32 v150, v244, v143
	v_cmp_gt_u32_e32 vcc, 16, v150
	v_add_u32_e32 v244, v148, v244
	s_and_b64 vcc, s[0:1], vcc
	v_cndmask_b32_e32 v244, 0, v244, vcc
	v_lshlrev_b32_e32 v244, 2, v244
	ds_read_b32 v244, v244 offset:35840
	v_or_b32_e32 v245, 9, v147
	v_sub_u32_e32 v150, v245, v143
	v_cmp_gt_u32_e32 vcc, 16, v150
	v_add_u32_e32 v245, v148, v245
	s_and_b64 vcc, s[0:1], vcc
	v_cndmask_b32_e32 v245, 0, v245, vcc
	v_lshlrev_b32_e32 v245, 2, v245
	ds_read_b32 v245, v245 offset:35840
	v_or_b32_e32 v246, 10, v147
	v_sub_u32_e32 v150, v246, v143
	v_cmp_gt_u32_e32 vcc, 16, v150
	v_add_u32_e32 v246, v148, v246
	s_and_b64 vcc, s[0:1], vcc
	v_cndmask_b32_e32 v246, 0, v246, vcc
	v_lshlrev_b32_e32 v246, 2, v246
	ds_read_b32 v246, v246 offset:35840
	v_or_b32_e32 v247, 11, v147
	v_sub_u32_e32 v150, v247, v143
	v_cmp_gt_u32_e32 vcc, 16, v150
	v_add_u32_e32 v247, v148, v247
	s_and_b64 vcc, s[0:1], vcc
	v_cndmask_b32_e32 v247, 0, v247, vcc
	v_lshlrev_b32_e32 v247, 2, v247
	ds_read_b32 v247, v247 offset:35840
	v_or_b32_e32 v248, 16, v147
	v_sub_u32_e32 v150, v248, v143
	v_cmp_gt_u32_e32 vcc, 16, v150
	v_add_u32_e32 v248, v148, v248
	s_and_b64 vcc, s[0:1], vcc
	v_cndmask_b32_e32 v248, 0, v248, vcc
	v_lshlrev_b32_e32 v248, 2, v248
	ds_read_b32 v248, v248 offset:35840
	v_or_b32_e32 v249, 17, v147
	v_sub_u32_e32 v150, v249, v143
	v_cmp_gt_u32_e32 vcc, 16, v150
	v_add_u32_e32 v249, v148, v249
	s_and_b64 vcc, s[0:1], vcc
	v_cndmask_b32_e32 v249, 0, v249, vcc
	v_lshlrev_b32_e32 v249, 2, v249
	ds_read_b32 v249, v249 offset:35840
	v_or_b32_e32 v250, 18, v147
	v_sub_u32_e32 v150, v250, v143
	v_cmp_gt_u32_e32 vcc, 16, v150
	v_add_u32_e32 v250, v148, v250
	s_and_b64 vcc, s[0:1], vcc
	v_cndmask_b32_e32 v250, 0, v250, vcc
	v_lshlrev_b32_e32 v250, 2, v250
	ds_read_b32 v250, v250 offset:35840
	v_or_b32_e32 v251, 19, v147
	v_sub_u32_e32 v150, v251, v143
	v_cmp_gt_u32_e32 vcc, 16, v150
	v_add_u32_e32 v251, v148, v251
	s_and_b64 vcc, s[0:1], vcc
	v_cndmask_b32_e32 v251, 0, v251, vcc
	v_lshlrev_b32_e32 v251, 2, v251
	ds_read_b32 v251, v251 offset:35840
	v_or_b32_e32 v252, 24, v147
	v_sub_u32_e32 v150, v252, v143
	v_cmp_gt_u32_e32 vcc, 16, v150
	v_add_u32_e32 v252, v148, v252
	s_and_b64 vcc, s[0:1], vcc
	v_cndmask_b32_e32 v252, 0, v252, vcc
	v_lshlrev_b32_e32 v252, 2, v252
	ds_read_b32 v252, v252 offset:35840
	v_or_b32_e32 v253, 25, v147
	v_sub_u32_e32 v150, v253, v143
	v_cmp_gt_u32_e32 vcc, 16, v150
	v_add_u32_e32 v253, v148, v253
	s_and_b64 vcc, s[0:1], vcc
	v_cndmask_b32_e32 v253, 0, v253, vcc
	v_lshlrev_b32_e32 v253, 2, v253
	ds_read_b32 v253, v253 offset:35840
	v_or_b32_e32 v254, 26, v147
	v_sub_u32_e32 v150, v254, v143
	v_cmp_gt_u32_e32 vcc, 16, v150
	v_add_u32_e32 v254, v148, v254
	s_and_b64 vcc, s[0:1], vcc
	v_cndmask_b32_e32 v254, 0, v254, vcc
	v_lshlrev_b32_e32 v254, 2, v254
	ds_read_b32 v254, v254 offset:35840
	v_or_b32_e32 v255, 27, v147
	v_sub_u32_e32 v150, v255, v143
	v_cmp_gt_u32_e32 vcc, 16, v150
	v_add_u32_e32 v255, v148, v255
	s_and_b64 vcc, s[0:1], vcc
	v_cndmask_b32_e32 v255, 0, v255, vcc
	v_lshlrev_b32_e32 v255, 2, v255
	ds_read_b32 v255, v255 offset:35840
	s_waitcnt lgkmcnt(0)
; #define MFMA32(a, b, c) __builtin_amdgcn_mfma_f32_32x32x16_bf16((a), (b), (c), 0, 0, 0)
; DI unsigned pk2(float a, float b) { f32x2 v = {a, b}; bf2_t r = __builtin_convertvector(v, bf2_t); return __builtin_bit_cast(unsigned, r); }
; template <int MODE>
; __device__ __forceinline__ void attn_item_BC(const Params& p, int layer, int head, int q0u, char* lds) {
;     ...
;     float w[16];
; #pragma unroll
;     for (int e = 0; e < 16; ++e) { w[e] = __builtin_amdgcn_exp2f(fmaf(sx[e], CS, -bsh)); lA += w[e]; }
;     const u32x4 p0 = {pk2(w[0], w[1]), pk2(w[2], w[3]), pk2(w[4], w[5]), pk2(w[6], w[7])};
;     const u32x4 p1 = {pk2(w[8], w[9]), pk2(w[10], w[11]), pk2(w[12], w[13]), pk2(w[14], w[15])};
;     const bf16x8 pa0 = __builtin_bit_cast(bf16x8, p0), pa1 = __builtin_bit_cast(bf16x8, p1);
;     const u16* vt = Vt + buf * 128 * VLD + r * VLD + 4 * h;
; #pragma unroll
;     for (int d = 0; d < 4; ++d) {
;       const s16x4 l0 = *(const s16x4*)(vt + d * 32 * VLD), h0 = *(const s16x4*)(vt + d * 32 * VLD + 8);
;       const s16x4 l1 = *(const s16x4*)(vt + d * 32 * VLD + 16), h1 = *(const s16x4*)(vt + d * 32 * VLD + 24);
;       const bf16x8 v0 = {l0[0], l0[1], l0[2], l0[3], h0[0], h0[1], h0[2], h0[3]};
;       const bf16x8 v1 = {l1[0], l1[1], l1[2], l1[3], h1[0], h1[1], h1[2], h1[3]};
;       o[d] = MFMA32(pa0, v0, o[d]);
;       o[d] = MFMA32(pa1, v1, o[d]);
;     }
;     if (more) { ATT_STOREK(buf ^ 1); ATT_STOREV(buf ^ 1); }
	v_mov_b32_e32 v149, v147
	v_sub_u32_e32 v150, v149, v143
	v_cmp_gt_u32_e32 vcc, 16, v150
	v_add_f32_e32 v64, v64, v240
	s_and_b64 vcc, s[0:1], vcc
	v_cndmask_b32_e32 v64, v188, v64, vcc
	v_or_b32_e32 v149, 1, v147
	v_sub_u32_e32 v150, v149, v143
	v_cmp_gt_u32_e32 vcc, 16, v150
	v_add_f32_e32 v65, v65, v241
	s_and_b64 vcc, s[0:1], vcc
	v_cndmask_b32_e32 v65, v188, v65, vcc
	v_or_b32_e32 v149, 2, v147
	v_sub_u32_e32 v150, v149, v143
	v_cmp_gt_u32_e32 vcc, 16, v150
	v_add_f32_e32 v66, v66, v242
	s_and_b64 vcc, s[0:1], vcc
	v_cndmask_b32_e32 v66, v188, v66, vcc
	v_or_b32_e32 v149, 3, v147
	v_sub_u32_e32 v150, v149, v143
	v_cmp_gt_u32_e32 vcc, 16, v150
	v_add_f32_e32 v67, v67, v243
	s_and_b64 vcc, s[0:1], vcc
	v_cndmask_b32_e32 v67, v188, v67, vcc
	v_or_b32_e32 v149, 8, v147
	v_sub_u32_e32 v150, v149, v143
	v_cmp_gt_u32_e32 vcc, 16, v150
	v_add_f32_e32 v68, v68, v244
	s_and_b64 vcc, s[0:1], vcc
	v_cndmask_b32_e32 v68, v188, v68, vcc
	v_or_b32_e32 v149, 9, v147
	v_sub_u32_e32 v150, v149, v143
	v_cmp_gt_u32_e32 vcc, 16, v150
	v_add_f32_e32 v69, v69, v245
	s_and_b64 vcc, s[0:1], vcc
	v_cndmask_b32_e32 v69, v188, v69, vcc
	v_or_b32_e32 v149, 10, v147
	v_sub_u32_e32 v150, v149, v143
	v_cmp_gt_u32_e32 vcc, 16, v150
	v_add_f32_e32 v70, v70, v246
	s_and_b64 vcc, s[0:1], vcc
	v_cndmask_b32_e32 v70, v188, v70, vcc
	v_or_b32_e32 v149, 11, v147
	v_sub_u32_e32 v150, v149, v143
	v_cmp_gt_u32_e32 vcc, 16, v150
	v_add_f32_e32 v71, v71, v247
	s_and_b64 vcc, s[0:1], vcc
	v_cndmask_b32_e32 v71, v188, v71, vcc
	v_or_b32_e32 v149, 16, v147
	v_sub_u32_e32 v150, v149, v143
	v_cmp_gt_u32_e32 vcc, 16, v150
	v_add_f32_e32 v72, v72, v248
	s_and_b64 vcc, s[0:1], vcc
	v_cndmask_b32_e32 v72, v188, v72, vcc
	v_or_b32_e32 v149, 17, v147
	v_sub_u32_e32 v150, v149, v143
	v_cmp_gt_u32_e32 vcc, 16, v150
	v_add_f32_e32 v73, v73, v249
	s_and_b64 vcc, s[0:1], vcc
	v_cndmask_b32_e32 v73, v188, v73, vcc
	v_or_b32_e32 v149, 18, v147
	v_sub_u32_e32 v150, v149, v143
	v_cmp_gt_u32_e32 vcc, 16, v150
	v_add_f32_e32 v74, v74, v250
	s_and_b64 vcc, s[0:1], vcc
	v_cndmask_b32_e32 v74, v188, v74, vcc
	v_or_b32_e32 v149, 19, v147
	v_sub_u32_e32 v150, v149, v143
	v_cmp_gt_u32_e32 vcc, 16, v150
	v_add_f32_e32 v75, v75, v251
	s_and_b64 vcc, s[0:1], vcc
	v_cndmask_b32_e32 v75, v188, v75, vcc
	v_or_b32_e32 v149, 24, v147
	v_sub_u32_e32 v150, v149, v143
	v_cmp_gt_u32_e32 vcc, 16, v150
	v_add_f32_e32 v76, v76, v252
	s_and_b64 vcc, s[0:1], vcc
	v_cndmask_b32_e32 v76, v188, v76, vcc
	v_or_b32_e32 v149, 25, v147
	v_sub_u32_e32 v150, v149, v143
	v_cmp_gt_u32_e32 vcc, 16, v150
	v_add_f32_e32 v77, v77, v253
	s_and_b64 vcc, s[0:1], vcc
	v_cndmask_b32_e32 v77, v188, v77, vcc
	v_or_b32_e32 v149, 26, v147
	v_sub_u32_e32 v150, v149, v143
	v_cmp_gt_u32_e32 vcc, 16, v150
	v_add_f32_e32 v78, v78, v254
	s_and_b64 vcc, s[0:1], vcc
	v_cndmask_b32_e32 v78, v188, v78, vcc
	v_or_b32_e32 v149, 27, v147
	v_sub_u32_e32 v150, v149, v143
	v_cmp_gt_u32_e32 vcc, 16, v150
	v_add_f32_e32 v79, v79, v255
	s_and_b64 vcc, s[0:1], vcc
	v_cndmask_b32_e32 v79, v188, v79, vcc
.LBB0_2305:
	v_fma_f32 v64, v64, s77, -v144
	v_fma_f32 v65, v65, s77, -v144
	v_fma_f32 v66, v66, s77, -v144
	v_fma_f32 v67, v67, s77, -v144
	v_fma_f32 v68, v68, s77, -v144
	v_fma_f32 v69, v69, s77, -v144
	v_fma_f32 v70, v70, s77, -v144
	v_fma_f32 v71, v71, s77, -v144
	v_exp_f32_e32 v64, v64
	v_exp_f32_e32 v65, v65
	v_exp_f32_e32 v66, v66
	v_exp_f32_e32 v67, v67
	v_exp_f32_e32 v68, v68
	v_exp_f32_e32 v69, v69
	v_exp_f32_e32 v70, v70
	v_exp_f32_e32 v71, v71
	s_mul_i32 s0, s52, 0x2400
	v_add_u32_e32 v147, s0, v146
	v_add_u32_e32 v160, 0x4000, v147
	v_cvt_pk_bf16_f32 v148, v64, v65
	v_cvt_pk_bf16_f32 v149, v66, v67
	v_cvt_pk_bf16_f32 v150, v68, v69
	v_cvt_pk_bf16_f32 v151, v70, v71
	ds_read2_b64 v[152:155], v160 offset0:128 offset1:130
	v_fma_f32 v72, v72, s77, -v144
	v_fma_f32 v73, v73, s77, -v144
	v_fma_f32 v74, v74, s77, -v144
	v_fma_f32 v75, v75, s77, -v144
	v_fma_f32 v76, v76, s77, -v144
	v_fma_f32 v77, v77, s77, -v144
	v_fma_f32 v78, v78, s77, -v144
	v_fma_f32 v79, v79, s77, -v144
	v_exp_f32_e32 v72, v72
	v_exp_f32_e32 v73, v73
	v_exp_f32_e32 v74, v74
	v_exp_f32_e32 v75, v75
	v_exp_f32_e32 v76, v76
	v_exp_f32_e32 v77, v77
	v_exp_f32_e32 v78, v78
	v_exp_f32_e32 v79, v79
	s_setprio 1
	s_waitcnt lgkmcnt(0)
	v_mfma_f32_32x32x16_bf16 v[48:63], v[148:151], v[152:155], v[48:63]
	v_cvt_pk_bf16_f32 v156, v72, v73
	v_cvt_pk_bf16_f32 v157, v74, v75
	v_cvt_pk_bf16_f32 v158, v76, v77
	v_cvt_pk_bf16_f32 v159, v78, v79
	ds_read2_b64 v[152:155], v160 offset0:132 offset1:134
	v_add_u32_e32 v160, 0x4800, v147
	s_andn2_b64 vcc, exec, s[6:7]
	s_waitcnt lgkmcnt(0)
	v_mfma_f32_32x32x16_bf16 v[48:63], v[156:159], v[152:155], v[48:63]
	ds_read2_b64 v[152:155], v160 offset0:160 offset1:162
	s_waitcnt lgkmcnt(0)
	v_mfma_f32_32x32x16_bf16 v[32:47], v[148:151], v[152:155], v[32:47]
	ds_read2_b64 v[152:155], v160 offset0:164 offset1:166
	v_add_u32_e32 v160, 0x5000, v147
	v_add_u32_e32 v147, 0x5800, v147
	s_waitcnt lgkmcnt(0)
	v_mfma_f32_32x32x16_bf16 v[32:47], v[156:159], v[152:155], v[32:47]
	ds_read2_b64 v[152:155], v160 offset0:192 offset1:194
	s_waitcnt lgkmcnt(0)
	v_mfma_f32_32x32x16_bf16 v[16:31], v[148:151], v[152:155], v[16:31]
	ds_read2_b64 v[152:155], v160 offset0:196 offset1:198
	s_waitcnt lgkmcnt(0)
	v_mfma_f32_32x32x16_bf16 v[16:31], v[156:159], v[152:155], v[16:31]
	ds_read2_b64 v[152:155], v147 offset0:224 offset1:226
	s_waitcnt lgkmcnt(0)
	v_mfma_f32_32x32x16_bf16 v[0:15], v[148:151], v[152:155], v[0:15]
	ds_read2_b64 v[148:151], v147 offset0:228 offset1:230
	s_waitcnt lgkmcnt(0)
	v_mfma_f32_32x32x16_bf16 v[0:15], v[156:159], v[148:151], v[0:15]
	s_setprio 0
	s_cbranch_vccnz .LBB0_2307
	s_xor_b32 s0, s52, 1
	s_mul_i32 s1, s0, 0x2200
	v_add_u32_e32 v147, s1, v130
	s_mulk_i32 s0, 0x2400
	s_waitcnt vmcnt(2)
	ds_write_b128 v147, v[116:119]
	ds_write_b128 v147, v[112:115] offset:16
	v_add_u32_e32 v147, s0, v132
	v_add_u32_e32 v148, 0x4400, v147
	v_add_u32_e32 v147, 0x4410, v147
	s_waitcnt vmcnt(0)
	ds_write2_b64 v148, v[124:125], v[126:127] offset1:1
	ds_write2_b64 v147, v[120:121], v[122:123] offset1:1

; #define MFMA32(a, b, c) __builtin_amdgcn_mfma_f32_32x32x16_bf16((a), (b), (c), 0, 0, 0)
; DI unsigned pk2(float a, float b) { f32x2 v = {a, b}; bf2_t r = __builtin_convertvector(v, bf2_t); return __builtin_bit_cast(unsigned, r); }
; template <int MODE>
; __device__ __forceinline__ void attn_item_BC(const Params& p, int layer, int head, int q0u, char* lds) {
;     ...
;     const int buf = t & 1;
;     const bool more = (t + 1 < ntiles);
;     if (more) { ATT_LOADK(t + 1); ATT_LOADV(t + 1); }
;     const bool local = t >= 8;
;     const int kp0 = lo + (t - 8) * 32;
;     f32x16 sx;
;     ATT_SCORES(sx, 0, 8);
;     float w[16];
; #pragma unroll
;     for (int e = 0; e < 16; ++e) { w[e] = __builtin_amdgcn_exp2f(fmaf(sx[e], CS, -bsh)); lA += w[e]; }
;     const u32x4 p0 = {pk2(w[0], w[1]), pk2(w[2], w[3]), pk2(w[4], w[5]), pk2(w[6], w[7])};
;     const u32x4 p1 = {pk2(w[8], w[9]), pk2(w[10], w[11]), pk2(w[12], w[13]), pk2(w[14], w[15])};
;     const bf16x8 pa0 = __builtin_bit_cast(bf16x8, p0), pa1 = __builtin_bit_cast(bf16x8, p1);
;     const u16* vt = Vt + buf * 128 * VLD + r * VLD + 4 * h;
; #pragma unroll
;     for (int d = 0; d < 4; ++d) {
;       const s16x4 l0 = *(const s16x4*)(vt + d * 32 * VLD), h0 = *(const s16x4*)(vt + d * 32 * VLD + 8);
;       const s16x4 l1 = *(const s16x4*)(vt + d * 32 * VLD + 16), h1 = *(const s16x4*)(vt + d * 32 * VLD + 24);
;       const bf16x8 v0 = {l0[0], l0[1], l0[2], l0[3], h0[0], h0[1], h0[2], h0[3]};
;       const bf16x8 v1 = {l1[0], l1[1], l1[2], l1[3], h1[0], h1[1], h1[2], h1[3]};
;       o[d] = MFMA32(pa0, v0, o[d]);
;       o[d] = MFMA32(pa1, v1, o[d]);
;     }
;     if (more) { ATT_STOREK(buf ^ 1); ATT_STOREV(buf ^ 1); }
.LBB0_2319:
	s_and_b32 s10, s4, 1
	s_mul_i32 s11, s10, 0x2200
	v_add_u32_e32 v145, s11, v142
	ds_read_b128 v[64:67], v145
	ds_read_b128 v[146:149], v145 offset:32
	s_cmp_gt_u32 s4, 7
	s_cselect_b64 s[4:5], -1, 0
	s_setprio 1
	s_waitcnt lgkmcnt(1)
	v_mfma_f32_32x32x16_bf16 v[64:79], v[64:67], v[80:83], 0
	s_waitcnt lgkmcnt(0)
	v_mfma_f32_32x32x16_bf16 v[64:79], v[146:149], v[84:87], v[64:79]
	ds_read_b128 v[146:149], v145 offset:64
	s_waitcnt lgkmcnt(0)
	v_mfma_f32_32x32x16_bf16 v[64:79], v[146:149], v[88:91], v[64:79]
	ds_read_b128 v[146:149], v145 offset:96
	s_waitcnt lgkmcnt(0)
	v_mfma_f32_32x32x16_bf16 v[64:79], v[146:149], v[92:95], v[64:79]
	ds_read_b128 v[146:149], v145 offset:128
	s_waitcnt lgkmcnt(0)
	v_mfma_f32_32x32x16_bf16 v[64:79], v[146:149], v[96:99], v[64:79]
	ds_read_b128 v[146:149], v145 offset:160
	s_waitcnt lgkmcnt(0)
	v_mfma_f32_32x32x16_bf16 v[64:79], v[146:149], v[100:103], v[64:79]
	ds_read_b128 v[146:149], v145 offset:192
	s_waitcnt lgkmcnt(0)
	v_mfma_f32_32x32x16_bf16 v[64:79], v[146:149], v[116:119], v[64:79]
	ds_read_b128 v[146:149], v145 offset:224
	v_add_u32_e32 v145, s8, v144
	s_waitcnt lgkmcnt(0)
	v_mfma_f32_32x32x16_bf16 v[64:79], v[146:149], v[104:107], v[64:79]
	s_setprio 0
	v_add_u32_e32 v146, 0xffffff7f, v145
	v_cmp_gt_u32_e32 vcc, s80, v146
	s_and_b64 vcc, s[4:5], vcc
	v_add_u32_e32 v146, 0xffffff80, v145
	s_nop 7
	v_cndmask_b32_e32 v64, v64, v188, vcc
	v_cmp_gt_u32_e32 vcc, s80, v146
	s_and_b64 vcc, s[4:5], vcc
	v_add_u32_e32 v146, 0xffffff81, v145
	v_cndmask_b32_e32 v65, v65, v188, vcc
	v_cmp_gt_u32_e32 vcc, s80, v146
	s_and_b64 vcc, s[4:5], vcc
	v_add_u32_e32 v146, 0xffffff82, v145
	v_cndmask_b32_e32 v66, v66, v188, vcc
	v_cmp_gt_u32_e32 vcc, s80, v146
	s_and_b64 vcc, s[4:5], vcc
	v_add_u32_e32 v146, 0xffffff87, v145
	v_cndmask_b32_e32 v67, v67, v188, vcc
	v_cmp_gt_u32_e32 vcc, s80, v146
	s_and_b64 vcc, s[4:5], vcc
	v_add_u32_e32 v146, 0xffffff88, v145
	v_cndmask_b32_e32 v68, v68, v188, vcc
	v_cmp_gt_u32_e32 vcc, s80, v146
	s_and_b64 vcc, s[4:5], vcc
	v_add_u32_e32 v146, 0xffffff89, v145
	v_cndmask_b32_e32 v69, v69, v188, vcc
	v_cmp_gt_u32_e32 vcc, s80, v146
	s_and_b64 vcc, s[4:5], vcc
	v_add_u32_e32 v146, 0xffffff8a, v145
	v_cndmask_b32_e32 v70, v70, v188, vcc
	v_cmp_gt_u32_e32 vcc, s80, v146
	s_and_b64 vcc, s[4:5], vcc
	v_add_u32_e32 v146, 0xffffff8f, v145
	v_cndmask_b32_e32 v71, v71, v188, vcc
	v_cmp_gt_u32_e32 vcc, s80, v146
	s_and_b64 vcc, s[4:5], vcc
	v_add_u32_e32 v146, 0xffffff90, v145
	v_cndmask_b32_e32 v72, v72, v188, vcc
	v_cmp_gt_u32_e32 vcc, s80, v146
	s_and_b64 vcc, s[4:5], vcc
	v_add_u32_e32 v146, 0xffffff91, v145
	v_cndmask_b32_e32 v73, v73, v188, vcc
	v_cmp_gt_u32_e32 vcc, s80, v146
	s_and_b64 vcc, s[4:5], vcc
	v_add_u32_e32 v146, 0xffffff92, v145
	v_cndmask_b32_e32 v74, v74, v188, vcc
	v_cmp_gt_u32_e32 vcc, s80, v146
	s_and_b64 vcc, s[4:5], vcc
	v_add_u32_e32 v146, 0xffffff97, v145
	v_cndmask_b32_e32 v75, v75, v188, vcc
	v_cmp_gt_u32_e32 vcc, s80, v146
	s_and_b64 vcc, s[4:5], vcc
	v_add_u32_e32 v146, 0xffffff98, v145
	v_cndmask_b32_e32 v76, v76, v188, vcc
	v_cmp_gt_u32_e32 vcc, s80, v146
	s_and_b64 vcc, s[4:5], vcc
	v_add_u32_e32 v146, 0xffffff99, v145
	v_cndmask_b32_e32 v77, v77, v188, vcc
	v_cmp_gt_u32_e32 vcc, s80, v146
	v_fma_f32 v64, v64, s77, -v139
	v_fma_f32 v65, v65, s77, -v139
	v_fma_f32 v66, v66, s77, -v139
	v_fma_f32 v67, v67, s77, -v139
	v_fma_f32 v68, v68, s77, -v139
	v_fma_f32 v69, v69, s77, -v139
	v_fma_f32 v70, v70, s77, -v139
	v_fma_f32 v71, v71, s77, -v139
	s_and_b64 vcc, s[4:5], vcc
	v_add_u32_e32 v145, 0xffffff9a, v145
	v_exp_f32_e32 v64, v64
	v_exp_f32_e32 v65, v65
	v_exp_f32_e32 v66, v66
	v_exp_f32_e32 v67, v67
	v_exp_f32_e32 v68, v68
	v_exp_f32_e32 v69, v69
	v_exp_f32_e32 v70, v70
	v_exp_f32_e32 v71, v71
	v_cndmask_b32_e32 v78, v78, v188, vcc
	v_cmp_gt_u32_e32 vcc, s80, v145
	s_and_b64 vcc, s[4:5], vcc
	s_mul_i32 s4, s10, 0x2400
	v_add_u32_e32 v145, s4, v143
	v_cvt_pk_bf16_f32 v146, v64, v65
	v_cvt_pk_bf16_f32 v147, v66, v67
	v_cvt_pk_bf16_f32 v148, v68, v69
	v_cvt_pk_bf16_f32 v149, v70, v71
	v_add_u32_e32 v158, 0x4000, v145
	ds_read2_b64 v[154:157], v158 offset0:128 offset1:130
	ds_read2_b64 v[158:161], v158 offset0:132 offset1:134
	v_cndmask_b32_e32 v79, v79, v188, vcc
	v_fma_f32 v72, v72, s77, -v139
	v_fma_f32 v73, v73, s77, -v139
	v_fma_f32 v74, v74, s77, -v139
	v_fma_f32 v75, v75, s77, -v139
	v_fma_f32 v76, v76, s77, -v139
	v_fma_f32 v77, v77, s77, -v139
	v_fma_f32 v78, v78, s77, -v139
	v_fma_f32 v79, v79, s77, -v139
	v_exp_f32_e32 v72, v72
	v_exp_f32_e32 v73, v73
	v_exp_f32_e32 v74, v74
	v_exp_f32_e32 v75, v75
	v_exp_f32_e32 v76, v76
	v_exp_f32_e32 v77, v77
	v_exp_f32_e32 v78, v78
	v_exp_f32_e32 v79, v79
	s_setprio 1
	s_waitcnt lgkmcnt(1)
	v_mfma_f32_32x32x16_bf16 v[48:63], v[146:149], v[154:157], v[48:63]
	v_cvt_pk_bf16_f32 v150, v72, v73
	v_cvt_pk_bf16_f32 v151, v74, v75
	v_cvt_pk_bf16_f32 v152, v76, v77
	v_cvt_pk_bf16_f32 v153, v78, v79
	s_andn2_b64 vcc, exec, s[0:1]
	s_waitcnt lgkmcnt(0)
	v_mfma_f32_32x32x16_bf16 v[48:63], v[150:153], v[158:161], v[48:63]
	v_add_u32_e32 v158, 0x4800, v145
	ds_read2_b64 v[154:157], v158 offset0:160 offset1:162
	ds_read2_b64 v[158:161], v158 offset0:164 offset1:166
	s_waitcnt lgkmcnt(1)
	v_mfma_f32_32x32x16_bf16 v[32:47], v[146:149], v[154:157], v[32:47]
	s_waitcnt lgkmcnt(0)
	v_mfma_f32_32x32x16_bf16 v[32:47], v[150:153], v[158:161], v[32:47]
	v_add_u32_e32 v158, 0x5000, v145
	ds_read2_b64 v[154:157], v158 offset0:192 offset1:194
	ds_read2_b64 v[158:161], v158 offset0:196 offset1:198
	v_add_u32_e32 v145, 0x5800, v145
	s_waitcnt lgkmcnt(1)
	v_mfma_f32_32x32x16_bf16 v[16:31], v[146:149], v[154:157], v[16:31]
	s_waitcnt lgkmcnt(0)
	v_mfma_f32_32x32x16_bf16 v[16:31], v[150:153], v[158:161], v[16:31]
	ds_read2_b64 v[154:157], v145 offset0:224 offset1:226
	ds_read2_b64 v[158:161], v145 offset0:228 offset1:230
	s_waitcnt lgkmcnt(1)
	v_mfma_f32_32x32x16_bf16 v[0:15], v[146:149], v[154:157], v[0:15]
	s_waitcnt lgkmcnt(0)
	v_mfma_f32_32x32x16_bf16 v[0:15], v[150:153], v[158:161], v[0:15]
	s_setprio 0
	s_cbranch_vccnz .LBB0_2321
	s_xor_b32 s0, s10, 1
	s_mul_i32 s1, s0, 0x2200
	v_add_u32_e32 v145, s1, v130
	s_mulk_i32 s0, 0x2400
	s_waitcnt vmcnt(2)
	ds_write_b128 v145, v[112:115]
	ds_write_b128 v145, v[108:111] offset:16
	v_add_u32_e32 v145, s0, v132
	v_add_u32_e32 v146, 0x4400, v145
	v_add_u32_e32 v145, 0x4410, v145
	s_waitcnt vmcnt(0)
	ds_write2_b64 v146, v[124:125], v[126:127] offset1:1
	ds_write2_b64 v145, v[120:121], v[122:123] offset1:1
